# ssd_m2 B/C-operand conv+SiLU rewritten by hand for all 512 threads (8 channels x 4 rows each), FMA chain as in the original
# baseline (speedup 1.0000x reference)
; #define LAS __attribute__((address_space(3)))
; #define TIDX opaque_tid()
; __device__ __forceinline__ u32x4 pack8(const float* f) { u32x4 w; w.x = pk2(f[0], f[1]); w.y = pk2(f[2], f[3]); w.z = pk2(f[4], f[5]); w.w = pk2(f[6], f[7]); return w; }
; template <class CM, class F>
; __device__ __forceinline__ void conv64(const bf16_t* proj, int row0, int tseq0, int pc0, const float* cw, const float* cb, int C, int nchunks, CM&& chmap, F&& emit) {
;     for (int u = TIDX; u < nchunks * 8; u += 512) {
;         const int q = u % nchunks, seg = u / nchunks, c = chmap(q), j0 = seg * 8;
;         const bf16_t* src = proj + (size_t)(row0 + j0) * NPROJ + pc0 + c;
;         u32x4 raw[11];
;         if (tseq0 + j0 == 0) { raw[0] = (u32x4){0u, 0u, 0u, 0u}; raw[1] = raw[0]; raw[2] = raw[0]; }
;         else { raw[0] = *(const u32x4*)(src - 3 * NPROJ); raw[1] = *(const u32x4*)(src - 2 * NPROJ); raw[2] = *(const u32x4*)(src - NPROJ); }
; #pragma unroll
;         for (int j = 0; j < 8; ++j) raw[3 + j] = *(const u32x4*)(src + (size_t)j * NPROJ);
;         float w0[8], w1[8], w2[8], w3[8], bb[8];
; #pragma unroll
;         for (int e = 0; e < 8; ++e) { w0[e] = cw[c + e]; w1[e] = cw[C + c + e]; w2[e] = cw[2 * C + c + e]; w3[e] = cw[3 * C + c + e]; bb[e] = cb[c + e]; }
;         float h3[8], h2[8], h1[8];
;         unpack8(raw[0], h3); unpack8(raw[1], h2); unpack8(raw[2], h1);
; #pragma unroll
;         for (int j = 0; j < 8; ++j) {
;             float cur[8], y[8];
;             unpack8(raw[3 + j], cur);
; #pragma unroll
;             for (int e = 0; e < 8; ++e) y[e] = bb[e] + w0[e] * h3[e] + w1[e] * h2[e] + w2[e] * h1[e] + w3[e] * cur[e];
;             emit(j0 + j, q, c, y);
; #pragma unroll
;             for (int e = 0; e < 8; ++e) { h3[e] = h2[e]; h2[e] = h1[e]; h1[e] = cur[e]; }
;         }
; __device__ void ssd_m2(const Params& p, LAS unsigned char* lds, int l, int b, int c, int g) {
;     ...
;     conv64(proj, row0, c * 64, PC_XBC, cw, cb, 1024, 32, [g](int q) { return (q < 16 ? 512 : 768 - 128) + g * 128 + q * 8; },
;            [&](int j, int q, int ch, float* y) {
;                float s[8];
; #pragma unroll
;                for (int e = 0; e < 8; ++e) s[e] = siluf_(y[e]);
;                if (q < 16) *(LAS u32x4*)(Bm + j * 136 + q * 8) = pack8(s); else *(LAS u32x4*)(Cm + j * 136 + (q - 16) * 8) = pack8(s);
;            });
.LBB0_306:
	s_or_b64 exec, exec, s[0:1]
	v_mov_b32_e32 v87, v163
	s_movk_i32 s0, 0x100
	s_waitcnt lgkmcnt(0)
	s_barrier
	s_mov_b64 s[0:1], exec
	v_and_b32_e32 v105, 31, v163
	v_lshrrev_b32_e32 v106, 5, v163
	v_lshlrev_b32_e32 v106, 2, v106
	s_lshl_b32 s36, s96, 7
	v_lshl_add_u32 v107, v105, 3, s36
	v_mov_b32_e32 v108, 0x200
	v_mov_b32_e32 v109, 0x280
	v_cmp_gt_u32_e32 vcc, 16, v105
	s_nop 1
	v_cndmask_b32_e32 v108, v109, v108, vcc
	v_add_u32_e32 v107, v107, v108
	v_add_u32_e32 v110, s30, v106
	v_add_u32_e32 v86, s26, v106
	v_add_u32_e32 v86, -3, v86
	v_ashrrev_i32_e32 v87, 31, v86
	v_lshlrev_b64 v[86:87], 13, v[86:87]
	v_lshl_add_u64 v[86:87], s[34:35], 0, v[86:87]
	v_lshlrev_b32_e32 v108, 1, v107
	v_mov_b32_e32 v109, 0
	v_lshl_add_u64 v[86:87], v[86:87], 0, v[108:109]
	s_mov_b64 s[40:41], 0x1800
	v_lshl_add_u64 v[86:87], v[86:87], 0, s[40:41]
	v_lshlrev_b32_e32 v108, 2, v107
	v_lshl_add_u64 v[88:89], s[22:23], 0, v[108:109]
	v_lshl_add_u64 v[90:91], s[38:39], 0, v[108:109]
	v_mov_b32_e32 v2, 0
	v_mov_b32_e32 v3, 0
	v_mov_b32_e32 v4, 0
	v_mov_b32_e32 v5, 0
	v_mov_b32_e32 v6, 0
	v_mov_b32_e32 v7, 0
	v_mov_b32_e32 v8, 0
	v_mov_b32_e32 v9, 0
	v_mov_b32_e32 v10, 0
	v_mov_b32_e32 v11, 0
	v_mov_b32_e32 v12, 0
	v_mov_b32_e32 v13, 0
	s_mov_b64 s[40:41], 0x2000
	v_cmp_le_i32_e32 vcc, 3, v110
	s_and_saveexec_b64 s[36:37], vcc
	global_load_dwordx4 v[2:5], v[86:87], off
	s_or_b64 exec, exec, s[36:37]
	v_lshl_add_u64 v[86:87], v[86:87], 0, s[40:41]
	v_cmp_le_i32_e32 vcc, 2, v110
	s_and_saveexec_b64 s[36:37], vcc
	global_load_dwordx4 v[6:9], v[86:87], off
	s_or_b64 exec, exec, s[36:37]
	v_lshl_add_u64 v[86:87], v[86:87], 0, s[40:41]
	v_cmp_le_i32_e32 vcc, 1, v110
	s_and_saveexec_b64 s[36:37], vcc
	global_load_dwordx4 v[10:13], v[86:87], off
	s_or_b64 exec, exec, s[36:37]
	v_lshl_add_u64 v[86:87], v[86:87], 0, s[40:41]
	global_load_dwordx4 v[14:17], v[86:87], off
	v_lshl_add_u64 v[86:87], v[86:87], 0, s[40:41]
	global_load_dwordx4 v[18:21], v[86:87], off
	v_lshl_add_u64 v[86:87], v[86:87], 0, s[40:41]
	global_load_dwordx4 v[22:25], v[86:87], off
	v_lshl_add_u64 v[86:87], v[86:87], 0, s[40:41]
	global_load_dwordx4 v[26:29], v[86:87], off
	s_mov_b64 s[40:41], 0x1000
	global_load_dwordx4 v[30:33], v[88:89], off
	global_load_dwordx4 v[34:37], v[88:89], off offset:16
	v_lshl_add_u64 v[88:89], v[88:89], 0, s[40:41]
	global_load_dwordx4 v[38:41], v[88:89], off
	global_load_dwordx4 v[42:45], v[88:89], off offset:16
	v_lshl_add_u64 v[88:89], v[88:89], 0, s[40:41]
	global_load_dwordx4 v[46:49], v[88:89], off
	global_load_dwordx4 v[50:53], v[88:89], off offset:16
	v_lshl_add_u64 v[88:89], v[88:89], 0, s[40:41]
	global_load_dwordx4 v[54:57], v[88:89], off
	global_load_dwordx4 v[58:61], v[88:89], off offset:16
	global_load_dwordx4 v[62:65], v[90:91], off
	global_load_dwordx4 v[66:69], v[90:91], off offset:16
	v_mov_b32_e32 v104, 0x4400
	v_cmp_gt_u32_e32 vcc, 16, v105
	s_nop 1
	v_cndmask_b32_e32 v104, 0, v104, vcc
	v_mul_u32_u24_e32 v108, 0x110, v106
	v_and_b32_e32 v109, 15, v105
	v_lshl_add_u32 v108, v109, 4, v108
	v_add_u32_e32 v104, v104, v108
	s_waitcnt vmcnt(0)
	v_lshlrev_b32_e32 v96, 16, v2
	v_fma_f32 v92, v30, v96, v62
	v_lshlrev_b32_e32 v96, 16, v6
	v_fmac_f32_e32 v92, v38, v96
	v_lshlrev_b32_e32 v96, 16, v10
	v_fmac_f32_e32 v92, v46, v96
	v_lshlrev_b32_e32 v96, 16, v14
	v_fmac_f32_e32 v92, v54, v96
	v_lshlrev_b32_e32 v97, 16, v6
	v_fma_f32 v93, v30, v97, v62
	v_lshlrev_b32_e32 v97, 16, v10
	v_fmac_f32_e32 v93, v38, v97
	v_lshlrev_b32_e32 v97, 16, v14
	v_fmac_f32_e32 v93, v46, v97
	v_lshlrev_b32_e32 v97, 16, v18
	v_fmac_f32_e32 v93, v54, v97
	v_lshlrev_b32_e32 v98, 16, v10
	v_fma_f32 v94, v30, v98, v62
	v_lshlrev_b32_e32 v98, 16, v14
	v_fmac_f32_e32 v94, v38, v98
	v_lshlrev_b32_e32 v98, 16, v18
	v_fmac_f32_e32 v94, v46, v98
	v_lshlrev_b32_e32 v98, 16, v22
	v_fmac_f32_e32 v94, v54, v98
	v_lshlrev_b32_e32 v99, 16, v14
	v_fma_f32 v95, v30, v99, v62
	v_lshlrev_b32_e32 v99, 16, v18
	v_fmac_f32_e32 v95, v38, v99
	v_lshlrev_b32_e32 v99, 16, v22
	v_fmac_f32_e32 v95, v46, v99
	v_lshlrev_b32_e32 v99, 16, v26
	v_fmac_f32_e32 v95, v54, v99
	v_mul_f32_e32 v96, 0xbfb8aa3b, v92
	v_mul_f32_e32 v97, 0xbfb8aa3b, v93
	v_mul_f32_e32 v98, 0xbfb8aa3b, v94
	v_mul_f32_e32 v99, 0xbfb8aa3b, v95
	v_exp_f32_e32 v96, v96
	v_exp_f32_e32 v97, v97
	v_exp_f32_e32 v98, v98
	v_exp_f32_e32 v99, v99
	v_add_f32_e32 v96, 1.0, v96
	v_add_f32_e32 v97, 1.0, v97
	v_add_f32_e32 v98, 1.0, v98
	v_add_f32_e32 v99, 1.0, v99
	v_rcp_f32_e32 v96, v96
	v_rcp_f32_e32 v97, v97
	v_rcp_f32_e32 v98, v98
	v_rcp_f32_e32 v99, v99
	v_mul_f32_e32 v100, v92, v96
	v_mul_f32_e32 v101, v93, v97
	v_mul_f32_e32 v102, v94, v98
	v_mul_f32_e32 v103, v95, v99
	v_and_b32_e32 v96, 0xffff0000, v2
	v_fma_f32 v92, v31, v96, v63
	v_and_b32_e32 v96, 0xffff0000, v6
	v_fmac_f32_e32 v92, v39, v96
	v_and_b32_e32 v96, 0xffff0000, v10
	v_fmac_f32_e32 v92, v47, v96
	v_and_b32_e32 v96, 0xffff0000, v14
	v_fmac_f32_e32 v92, v55, v96
	v_and_b32_e32 v97, 0xffff0000, v6
	v_fma_f32 v93, v31, v97, v63
	v_and_b32_e32 v97, 0xffff0000, v10
	v_fmac_f32_e32 v93, v39, v97
	v_and_b32_e32 v97, 0xffff0000, v14
	v_fmac_f32_e32 v93, v47, v97
	v_and_b32_e32 v97, 0xffff0000, v18
	v_fmac_f32_e32 v93, v55, v97
	v_and_b32_e32 v98, 0xffff0000, v10
	v_fma_f32 v94, v31, v98, v63
	v_and_b32_e32 v98, 0xffff0000, v14
	v_fmac_f32_e32 v94, v39, v98
	v_and_b32_e32 v98, 0xffff0000, v18
	v_fmac_f32_e32 v94, v47, v98
	v_and_b32_e32 v98, 0xffff0000, v22
	v_fmac_f32_e32 v94, v55, v98
	v_and_b32_e32 v99, 0xffff0000, v14
	v_fma_f32 v95, v31, v99, v63
	v_and_b32_e32 v99, 0xffff0000, v18
	v_fmac_f32_e32 v95, v39, v99
	v_and_b32_e32 v99, 0xffff0000, v22
	v_fmac_f32_e32 v95, v47, v99
; #define LAS __attribute__((address_space(3)))
; #define TIDX opaque_tid()
; __device__ __forceinline__ u32x4 pack8(const float* f) { u32x4 w; w.x = pk2(f[0], f[1]); w.y = pk2(f[2], f[3]); w.z = pk2(f[4], f[5]); w.w = pk2(f[6], f[7]); return w; }
; template <class CM, class F>
; __device__ __forceinline__ void conv64(const bf16_t* proj, int row0, int tseq0, int pc0, const float* cw, const float* cb, int C, int nchunks, CM&& chmap, F&& emit) {
;     for (int u = TIDX; u < nchunks * 8; u += 512) {
;         const int q = u % nchunks, seg = u / nchunks, c = chmap(q), j0 = seg * 8;
;         const bf16_t* src = proj + (size_t)(row0 + j0) * NPROJ + pc0 + c;
;         u32x4 raw[11];
;         if (tseq0 + j0 == 0) { raw[0] = (u32x4){0u, 0u, 0u, 0u}; raw[1] = raw[0]; raw[2] = raw[0]; }
;         else { raw[0] = *(const u32x4*)(src - 3 * NPROJ); raw[1] = *(const u32x4*)(src - 2 * NPROJ); raw[2] = *(const u32x4*)(src - NPROJ); }
; #pragma unroll
;         for (int j = 0; j < 8; ++j) raw[3 + j] = *(const u32x4*)(src + (size_t)j * NPROJ);
;         float w0[8], w1[8], w2[8], w3[8], bb[8];
; #pragma unroll
;         for (int e = 0; e < 8; ++e) { w0[e] = cw[c + e]; w1[e] = cw[C + c + e]; w2[e] = cw[2 * C + c + e]; w3[e] = cw[3 * C + c + e]; bb[e] = cb[c + e]; }
;         float h3[8], h2[8], h1[8];
;         unpack8(raw[0], h3); unpack8(raw[1], h2); unpack8(raw[2], h1);
; #pragma unroll
;         for (int j = 0; j < 8; ++j) {
;             float cur[8], y[8];
;             unpack8(raw[3 + j], cur);
; #pragma unroll
;             for (int e = 0; e < 8; ++e) y[e] = bb[e] + w0[e] * h3[e] + w1[e] * h2[e] + w2[e] * h1[e] + w3[e] * cur[e];
;             emit(j0 + j, q, c, y);
; #pragma unroll
;             for (int e = 0; e < 8; ++e) { h3[e] = h2[e]; h2[e] = h1[e]; h1[e] = cur[e]; }
;         }
; __device__ void ssd_m2(const Params& p, LAS unsigned char* lds, int l, int b, int c, int g) {
;     ...
;     conv64(proj, row0, c * 64, PC_XBC, cw, cb, 1024, 32, [g](int q) { return (q < 16 ? 512 : 768 - 128) + g * 128 + q * 8; },
;            [&](int j, int q, int ch, float* y) {
;                float s[8];
; #pragma unroll
;                for (int e = 0; e < 8; ++e) s[e] = siluf_(y[e]);
;                if (q < 16) *(LAS u32x4*)(Bm + j * 136 + q * 8) = pack8(s); else *(LAS u32x4*)(Cm + j * 136 + (q - 16) * 8) = pack8(s);
;            });
	v_and_b32_e32 v99, 0xffff0000, v26
	v_fmac_f32_e32 v95, v55, v99
	v_mul_f32_e32 v96, 0xbfb8aa3b, v92
	v_mul_f32_e32 v97, 0xbfb8aa3b, v93
	v_mul_f32_e32 v98, 0xbfb8aa3b, v94
	v_mul_f32_e32 v99, 0xbfb8aa3b, v95
	v_exp_f32_e32 v96, v96
	v_exp_f32_e32 v97, v97
	v_exp_f32_e32 v98, v98
	v_exp_f32_e32 v99, v99
	v_add_f32_e32 v96, 1.0, v96
	v_add_f32_e32 v97, 1.0, v97
	v_add_f32_e32 v98, 1.0, v98
	v_add_f32_e32 v99, 1.0, v99
	v_rcp_f32_e32 v96, v96
	v_rcp_f32_e32 v97, v97
	v_rcp_f32_e32 v98, v98
	v_rcp_f32_e32 v99, v99
	v_mul_f32_e32 v92, v92, v96
	v_cvt_pk_bf16_f32 v70, v100, v92
	v_mul_f32_e32 v93, v93, v97
	v_cvt_pk_bf16_f32 v74, v101, v93
	v_mul_f32_e32 v94, v94, v98
	v_cvt_pk_bf16_f32 v78, v102, v94
	v_mul_f32_e32 v95, v95, v99
	v_cvt_pk_bf16_f32 v82, v103, v95
	v_lshlrev_b32_e32 v96, 16, v3
	v_fma_f32 v92, v32, v96, v64
	v_lshlrev_b32_e32 v96, 16, v7
	v_fmac_f32_e32 v92, v40, v96
	v_lshlrev_b32_e32 v96, 16, v11
	v_fmac_f32_e32 v92, v48, v96
	v_lshlrev_b32_e32 v96, 16, v15
	v_fmac_f32_e32 v92, v56, v96
	v_lshlrev_b32_e32 v97, 16, v7
	v_fma_f32 v93, v32, v97, v64
	v_lshlrev_b32_e32 v97, 16, v11
	v_fmac_f32_e32 v93, v40, v97
	v_lshlrev_b32_e32 v97, 16, v15
	v_fmac_f32_e32 v93, v48, v97
	v_lshlrev_b32_e32 v97, 16, v19
	v_fmac_f32_e32 v93, v56, v97
	v_lshlrev_b32_e32 v98, 16, v11
	v_fma_f32 v94, v32, v98, v64
	v_lshlrev_b32_e32 v98, 16, v15
	v_fmac_f32_e32 v94, v40, v98
	v_lshlrev_b32_e32 v98, 16, v19
	v_fmac_f32_e32 v94, v48, v98
	v_lshlrev_b32_e32 v98, 16, v23
	v_fmac_f32_e32 v94, v56, v98
	v_lshlrev_b32_e32 v99, 16, v15
	v_fma_f32 v95, v32, v99, v64
	v_lshlrev_b32_e32 v99, 16, v19
	v_fmac_f32_e32 v95, v40, v99
	v_lshlrev_b32_e32 v99, 16, v23
	v_fmac_f32_e32 v95, v48, v99
	v_lshlrev_b32_e32 v99, 16, v27
	v_fmac_f32_e32 v95, v56, v99
	v_mul_f32_e32 v96, 0xbfb8aa3b, v92
	v_mul_f32_e32 v97, 0xbfb8aa3b, v93
	v_mul_f32_e32 v98, 0xbfb8aa3b, v94
	v_mul_f32_e32 v99, 0xbfb8aa3b, v95
	v_exp_f32_e32 v96, v96
	v_exp_f32_e32 v97, v97
	v_exp_f32_e32 v98, v98
	v_exp_f32_e32 v99, v99
	v_add_f32_e32 v96, 1.0, v96
	v_add_f32_e32 v97, 1.0, v97
	v_add_f32_e32 v98, 1.0, v98
	v_add_f32_e32 v99, 1.0, v99
	v_rcp_f32_e32 v96, v96
	v_rcp_f32_e32 v97, v97
	v_rcp_f32_e32 v98, v98
	v_rcp_f32_e32 v99, v99
	v_mul_f32_e32 v100, v92, v96
	v_mul_f32_e32 v101, v93, v97
	v_mul_f32_e32 v102, v94, v98
	v_mul_f32_e32 v103, v95, v99
	v_and_b32_e32 v96, 0xffff0000, v3
	v_fma_f32 v92, v33, v96, v65
	v_and_b32_e32 v96, 0xffff0000, v7
	v_fmac_f32_e32 v92, v41, v96
	v_and_b32_e32 v96, 0xffff0000, v11
	v_fmac_f32_e32 v92, v49, v96
	v_and_b32_e32 v96, 0xffff0000, v15
	v_fmac_f32_e32 v92, v57, v96
	v_and_b32_e32 v97, 0xffff0000, v7
	v_fma_f32 v93, v33, v97, v65
	v_and_b32_e32 v97, 0xffff0000, v11
	v_fmac_f32_e32 v93, v41, v97
	v_and_b32_e32 v97, 0xffff0000, v15
	v_fmac_f32_e32 v93, v49, v97
	v_and_b32_e32 v97, 0xffff0000, v19
	v_fmac_f32_e32 v93, v57, v97
	v_and_b32_e32 v98, 0xffff0000, v11
	v_fma_f32 v94, v33, v98, v65
	v_and_b32_e32 v98, 0xffff0000, v15
	v_fmac_f32_e32 v94, v41, v98
	v_and_b32_e32 v98, 0xffff0000, v19
	v_fmac_f32_e32 v94, v49, v98
	v_and_b32_e32 v98, 0xffff0000, v23
	v_fmac_f32_e32 v94, v57, v98
	v_and_b32_e32 v99, 0xffff0000, v15
	v_fma_f32 v95, v33, v99, v65
	v_and_b32_e32 v99, 0xffff0000, v19
	v_fmac_f32_e32 v95, v41, v99
	v_and_b32_e32 v99, 0xffff0000, v23
	v_fmac_f32_e32 v95, v49, v99
	v_and_b32_e32 v99, 0xffff0000, v27
	v_fmac_f32_e32 v95, v57, v99
	v_mul_f32_e32 v96, 0xbfb8aa3b, v92
	v_mul_f32_e32 v97, 0xbfb8aa3b, v93
	v_mul_f32_e32 v98, 0xbfb8aa3b, v94
	v_mul_f32_e32 v99, 0xbfb8aa3b, v95
	v_exp_f32_e32 v96, v96
	v_exp_f32_e32 v97, v97
	v_exp_f32_e32 v98, v98
	v_exp_f32_e32 v99, v99
	v_add_f32_e32 v96, 1.0, v96
	v_add_f32_e32 v97, 1.0, v97
	v_add_f32_e32 v98, 1.0, v98
	v_add_f32_e32 v99, 1.0, v99
	v_rcp_f32_e32 v96, v96
	v_rcp_f32_e32 v97, v97
	v_rcp_f32_e32 v98, v98
	v_rcp_f32_e32 v99, v99
	v_mul_f32_e32 v92, v92, v96
	v_cvt_pk_bf16_f32 v71, v100, v92
	v_mul_f32_e32 v93, v93, v97
	v_cvt_pk_bf16_f32 v75, v101, v93
	v_mul_f32_e32 v94, v94, v98
	v_cvt_pk_bf16_f32 v79, v102, v94
	v_mul_f32_e32 v95, v95, v99
	v_cvt_pk_bf16_f32 v83, v103, v95
	v_lshlrev_b32_e32 v96, 16, v4
	v_fma_f32 v92, v34, v96, v66
	v_lshlrev_b32_e32 v96, 16, v8
	v_fmac_f32_e32 v92, v42, v96
	v_lshlrev_b32_e32 v96, 16, v12
	v_fmac_f32_e32 v92, v50, v96
	v_lshlrev_b32_e32 v96, 16, v16
	v_fmac_f32_e32 v92, v58, v96
	v_lshlrev_b32_e32 v97, 16, v8
	v_fma_f32 v93, v34, v97, v66
	v_lshlrev_b32_e32 v97, 16, v12
	v_fmac_f32_e32 v93, v42, v97
	v_lshlrev_b32_e32 v97, 16, v16
	v_fmac_f32_e32 v93, v50, v97
	v_lshlrev_b32_e32 v97, 16, v20
	v_fmac_f32_e32 v93, v58, v97
	v_lshlrev_b32_e32 v98, 16, v12
	v_fma_f32 v94, v34, v98, v66
	v_lshlrev_b32_e32 v98, 16, v16
	v_fmac_f32_e32 v94, v42, v98
	v_lshlrev_b32_e32 v98, 16, v20
	v_fmac_f32_e32 v94, v50, v98
	v_lshlrev_b32_e32 v98, 16, v24
	v_fmac_f32_e32 v94, v58, v98
	v_lshlrev_b32_e32 v99, 16, v16
	v_fma_f32 v95, v34, v99, v66
	v_lshlrev_b32_e32 v99, 16, v20
	v_fmac_f32_e32 v95, v42, v99
	v_lshlrev_b32_e32 v99, 16, v24
	v_fmac_f32_e32 v95, v50, v99
	v_lshlrev_b32_e32 v99, 16, v28
	v_fmac_f32_e32 v95, v58, v99
	v_mul_f32_e32 v96, 0xbfb8aa3b, v92
	v_mul_f32_e32 v97, 0xbfb8aa3b, v93
	v_mul_f32_e32 v98, 0xbfb8aa3b, v94
	v_mul_f32_e32 v99, 0xbfb8aa3b, v95
	v_exp_f32_e32 v96, v96
	v_exp_f32_e32 v97, v97
	v_exp_f32_e32 v98, v98
	v_exp_f32_e32 v99, v99
	v_add_f32_e32 v96, 1.0, v96
	v_add_f32_e32 v97, 1.0, v97
	v_add_f32_e32 v98, 1.0, v98
	v_add_f32_e32 v99, 1.0, v99
	v_rcp_f32_e32 v96, v96
; #define LAS __attribute__((address_space(3)))
; #define TIDX opaque_tid()
; __device__ __forceinline__ u32x4 pack8(const float* f) { u32x4 w; w.x = pk2(f[0], f[1]); w.y = pk2(f[2], f[3]); w.z = pk2(f[4], f[5]); w.w = pk2(f[6], f[7]); return w; }
; template <class CM, class F>
; __device__ __forceinline__ void conv64(const bf16_t* proj, int row0, int tseq0, int pc0, const float* cw, const float* cb, int C, int nchunks, CM&& chmap, F&& emit) {
;     for (int u = TIDX; u < nchunks * 8; u += 512) {
;         const int q = u % nchunks, seg = u / nchunks, c = chmap(q), j0 = seg * 8;
;         const bf16_t* src = proj + (size_t)(row0 + j0) * NPROJ + pc0 + c;
;         u32x4 raw[11];
;         if (tseq0 + j0 == 0) { raw[0] = (u32x4){0u, 0u, 0u, 0u}; raw[1] = raw[0]; raw[2] = raw[0]; }
;         else { raw[0] = *(const u32x4*)(src - 3 * NPROJ); raw[1] = *(const u32x4*)(src - 2 * NPROJ); raw[2] = *(const u32x4*)(src - NPROJ); }
; #pragma unroll
;         for (int j = 0; j < 8; ++j) raw[3 + j] = *(const u32x4*)(src + (size_t)j * NPROJ);
;         float w0[8], w1[8], w2[8], w3[8], bb[8];
; #pragma unroll
;         for (int e = 0; e < 8; ++e) { w0[e] = cw[c + e]; w1[e] = cw[C + c + e]; w2[e] = cw[2 * C + c + e]; w3[e] = cw[3 * C + c + e]; bb[e] = cb[c + e]; }
;         float h3[8], h2[8], h1[8];
;         unpack8(raw[0], h3); unpack8(raw[1], h2); unpack8(raw[2], h1);
; #pragma unroll
;         for (int j = 0; j < 8; ++j) {
;             float cur[8], y[8];
;             unpack8(raw[3 + j], cur);
; #pragma unroll
;             for (int e = 0; e < 8; ++e) y[e] = bb[e] + w0[e] * h3[e] + w1[e] * h2[e] + w2[e] * h1[e] + w3[e] * cur[e];
;             emit(j0 + j, q, c, y);
; #pragma unroll
;             for (int e = 0; e < 8; ++e) { h3[e] = h2[e]; h2[e] = h1[e]; h1[e] = cur[e]; }
;         }
; __device__ void ssd_m2(const Params& p, LAS unsigned char* lds, int l, int b, int c, int g) {
;     ...
;     conv64(proj, row0, c * 64, PC_XBC, cw, cb, 1024, 32, [g](int q) { return (q < 16 ? 512 : 768 - 128) + g * 128 + q * 8; },
;            [&](int j, int q, int ch, float* y) {
;                float s[8];
; #pragma unroll
;                for (int e = 0; e < 8; ++e) s[e] = siluf_(y[e]);
;                if (q < 16) *(LAS u32x4*)(Bm + j * 136 + q * 8) = pack8(s); else *(LAS u32x4*)(Cm + j * 136 + (q - 16) * 8) = pack8(s);
;            });
	v_rcp_f32_e32 v97, v97
	v_rcp_f32_e32 v98, v98
	v_rcp_f32_e32 v99, v99
	v_mul_f32_e32 v100, v92, v96
	v_mul_f32_e32 v101, v93, v97
	v_mul_f32_e32 v102, v94, v98
	v_mul_f32_e32 v103, v95, v99
	v_and_b32_e32 v96, 0xffff0000, v4
	v_fma_f32 v92, v35, v96, v67
	v_and_b32_e32 v96, 0xffff0000, v8
	v_fmac_f32_e32 v92, v43, v96
	v_and_b32_e32 v96, 0xffff0000, v12
	v_fmac_f32_e32 v92, v51, v96
	v_and_b32_e32 v96, 0xffff0000, v16
	v_fmac_f32_e32 v92, v59, v96
	v_and_b32_e32 v97, 0xffff0000, v8
	v_fma_f32 v93, v35, v97, v67
	v_and_b32_e32 v97, 0xffff0000, v12
	v_fmac_f32_e32 v93, v43, v97
	v_and_b32_e32 v97, 0xffff0000, v16
	v_fmac_f32_e32 v93, v51, v97
	v_and_b32_e32 v97, 0xffff0000, v20
	v_fmac_f32_e32 v93, v59, v97
	v_and_b32_e32 v98, 0xffff0000, v12
	v_fma_f32 v94, v35, v98, v67
	v_and_b32_e32 v98, 0xffff0000, v16
	v_fmac_f32_e32 v94, v43, v98
	v_and_b32_e32 v98, 0xffff0000, v20
	v_fmac_f32_e32 v94, v51, v98
	v_and_b32_e32 v98, 0xffff0000, v24
	v_fmac_f32_e32 v94, v59, v98
	v_and_b32_e32 v99, 0xffff0000, v16
	v_fma_f32 v95, v35, v99, v67
	v_and_b32_e32 v99, 0xffff0000, v20
	v_fmac_f32_e32 v95, v43, v99
	v_and_b32_e32 v99, 0xffff0000, v24
	v_fmac_f32_e32 v95, v51, v99
	v_and_b32_e32 v99, 0xffff0000, v28
	v_fmac_f32_e32 v95, v59, v99
	v_mul_f32_e32 v96, 0xbfb8aa3b, v92
	v_mul_f32_e32 v97, 0xbfb8aa3b, v93
	v_mul_f32_e32 v98, 0xbfb8aa3b, v94
	v_mul_f32_e32 v99, 0xbfb8aa3b, v95
	v_exp_f32_e32 v96, v96
	v_exp_f32_e32 v97, v97
	v_exp_f32_e32 v98, v98
	v_exp_f32_e32 v99, v99
	v_add_f32_e32 v96, 1.0, v96
	v_add_f32_e32 v97, 1.0, v97
	v_add_f32_e32 v98, 1.0, v98
	v_add_f32_e32 v99, 1.0, v99
	v_rcp_f32_e32 v96, v96
	v_rcp_f32_e32 v97, v97
	v_rcp_f32_e32 v98, v98
	v_rcp_f32_e32 v99, v99
	v_mul_f32_e32 v92, v92, v96
	v_cvt_pk_bf16_f32 v72, v100, v92
	v_mul_f32_e32 v93, v93, v97
	v_cvt_pk_bf16_f32 v76, v101, v93
	v_mul_f32_e32 v94, v94, v98
	v_cvt_pk_bf16_f32 v80, v102, v94
	v_mul_f32_e32 v95, v95, v99
	v_cvt_pk_bf16_f32 v84, v103, v95
	v_lshlrev_b32_e32 v96, 16, v5
	v_fma_f32 v92, v36, v96, v68
	v_lshlrev_b32_e32 v96, 16, v9
	v_fmac_f32_e32 v92, v44, v96
	v_lshlrev_b32_e32 v96, 16, v13
	v_fmac_f32_e32 v92, v52, v96
	v_lshlrev_b32_e32 v96, 16, v17
	v_fmac_f32_e32 v92, v60, v96
	v_lshlrev_b32_e32 v97, 16, v9
	v_fma_f32 v93, v36, v97, v68
	v_lshlrev_b32_e32 v97, 16, v13
	v_fmac_f32_e32 v93, v44, v97
	v_lshlrev_b32_e32 v97, 16, v17
	v_fmac_f32_e32 v93, v52, v97
	v_lshlrev_b32_e32 v97, 16, v21
	v_fmac_f32_e32 v93, v60, v97
	v_lshlrev_b32_e32 v98, 16, v13
	v_fma_f32 v94, v36, v98, v68
	v_lshlrev_b32_e32 v98, 16, v17
	v_fmac_f32_e32 v94, v44, v98
	v_lshlrev_b32_e32 v98, 16, v21
	v_fmac_f32_e32 v94, v52, v98
	v_lshlrev_b32_e32 v98, 16, v25
	v_fmac_f32_e32 v94, v60, v98
	v_lshlrev_b32_e32 v99, 16, v17
	v_fma_f32 v95, v36, v99, v68
	v_lshlrev_b32_e32 v99, 16, v21
	v_fmac_f32_e32 v95, v44, v99
	v_lshlrev_b32_e32 v99, 16, v25
	v_fmac_f32_e32 v95, v52, v99
	v_lshlrev_b32_e32 v99, 16, v29
	v_fmac_f32_e32 v95, v60, v99
	v_mul_f32_e32 v96, 0xbfb8aa3b, v92
	v_mul_f32_e32 v97, 0xbfb8aa3b, v93
	v_mul_f32_e32 v98, 0xbfb8aa3b, v94
	v_mul_f32_e32 v99, 0xbfb8aa3b, v95
	v_exp_f32_e32 v96, v96
	v_exp_f32_e32 v97, v97
	v_exp_f32_e32 v98, v98
	v_exp_f32_e32 v99, v99
	v_add_f32_e32 v96, 1.0, v96
	v_add_f32_e32 v97, 1.0, v97
	v_add_f32_e32 v98, 1.0, v98
	v_add_f32_e32 v99, 1.0, v99
	v_rcp_f32_e32 v96, v96
	v_rcp_f32_e32 v97, v97
	v_rcp_f32_e32 v98, v98
	v_rcp_f32_e32 v99, v99
	v_mul_f32_e32 v100, v92, v96
	v_mul_f32_e32 v101, v93, v97
	v_mul_f32_e32 v102, v94, v98
	v_mul_f32_e32 v103, v95, v99
	v_and_b32_e32 v96, 0xffff0000, v5
	v_fma_f32 v92, v37, v96, v69
	v_and_b32_e32 v96, 0xffff0000, v9
	v_fmac_f32_e32 v92, v45, v96
	v_and_b32_e32 v96, 0xffff0000, v13
	v_fmac_f32_e32 v92, v53, v96
	v_and_b32_e32 v96, 0xffff0000, v17
	v_fmac_f32_e32 v92, v61, v96
	v_and_b32_e32 v97, 0xffff0000, v9
	v_fma_f32 v93, v37, v97, v69
	v_and_b32_e32 v97, 0xffff0000, v13
	v_fmac_f32_e32 v93, v45, v97
	v_and_b32_e32 v97, 0xffff0000, v17
	v_fmac_f32_e32 v93, v53, v97
	v_and_b32_e32 v97, 0xffff0000, v21
	v_fmac_f32_e32 v93, v61, v97
	v_and_b32_e32 v98, 0xffff0000, v13
	v_fma_f32 v94, v37, v98, v69
	v_and_b32_e32 v98, 0xffff0000, v17
	v_fmac_f32_e32 v94, v45, v98
	v_and_b32_e32 v98, 0xffff0000, v21
	v_fmac_f32_e32 v94, v53, v98
	v_and_b32_e32 v98, 0xffff0000, v25
	v_fmac_f32_e32 v94, v61, v98
	v_and_b32_e32 v99, 0xffff0000, v17
	v_fma_f32 v95, v37, v99, v69
	v_and_b32_e32 v99, 0xffff0000, v21
	v_fmac_f32_e32 v95, v45, v99
	v_and_b32_e32 v99, 0xffff0000, v25
	v_fmac_f32_e32 v95, v53, v99
	v_and_b32_e32 v99, 0xffff0000, v29
	v_fmac_f32_e32 v95, v61, v99
	v_mul_f32_e32 v96, 0xbfb8aa3b, v92
	v_mul_f32_e32 v97, 0xbfb8aa3b, v93
	v_mul_f32_e32 v98, 0xbfb8aa3b, v94
	v_mul_f32_e32 v99, 0xbfb8aa3b, v95
	v_exp_f32_e32 v96, v96
	v_exp_f32_e32 v97, v97
	v_exp_f32_e32 v98, v98
	v_exp_f32_e32 v99, v99
	v_add_f32_e32 v96, 1.0, v96
	v_add_f32_e32 v97, 1.0, v97
	v_add_f32_e32 v98, 1.0, v98
	v_add_f32_e32 v99, 1.0, v99
	v_rcp_f32_e32 v96, v96
	v_rcp_f32_e32 v97, v97
	v_rcp_f32_e32 v98, v98
	v_rcp_f32_e32 v99, v99
	v_mul_f32_e32 v92, v92, v96
	v_cvt_pk_bf16_f32 v73, v100, v92
	v_mul_f32_e32 v93, v93, v97
	v_cvt_pk_bf16_f32 v77, v101, v93
	v_mul_f32_e32 v94, v94, v98
	v_cvt_pk_bf16_f32 v81, v102, v94
	v_mul_f32_e32 v95, v95, v99
	v_cvt_pk_bf16_f32 v85, v103, v95
	ds_write_b128 v104, v[70:73]
	ds_write_b128 v104, v[74:77] offset:272
	ds_write_b128 v104, v[78:81] offset:544
	ds_write_b128 v104, v[82:85] offset:816
	s_waitcnt lgkmcnt(0)
